# phase 0: the adaLN bias value is requested ahead of the GEMV weight stream instead of after the reduction
# baseline (speedup 1.0000x reference)
.LBB0_29:
	s_lshl_b64 s[98:99], s[12:13], 2
	s_add_u32 s98, s98, s4
	s_addc_u32 s99, s99, s5
	v_add_u32_e32 v200, v20, v22
	ds_read_b64 v[202:203], v23 offset:152
	s_mul_i32 s100, s39, 0x1800
	s_add_i32 s100, s100, s12
	v_or_b32_e32 v204, s100, v198
	v_lshlrev_b32_e32 v204, 2, v204
	s_waitcnt lgkmcnt(0)
	v_readfirstlane_b32 s100, v202
	v_readfirstlane_b32 s101, v203
	s_nop 4
	global_load_dword v201, v204, s[100:101]
	global_load_dword v80, v200, s[98:99]
	s_add_u32 s98, s98, 0x6000
	s_addc_u32 s99, s99, 0
	global_load_dword v81, v200, s[98:99]
	s_add_u32 s98, s98, 0x6000
	s_addc_u32 s99, s99, 0
	global_load_dword v82, v200, s[98:99]
	s_add_u32 s98, s98, 0x6000
	s_addc_u32 s99, s99, 0
	global_load_dword v83, v200, s[98:99]
	s_add_u32 s98, s98, 0x6000
	s_addc_u32 s99, s99, 0
	global_load_dword v84, v200, s[98:99]
	s_add_u32 s98, s98, 0x6000
	s_addc_u32 s99, s99, 0
	global_load_dword v85, v200, s[98:99]
	s_add_u32 s98, s98, 0x6000
	s_addc_u32 s99, s99, 0
	global_load_dword v86, v200, s[98:99]
	s_add_u32 s98, s98, 0x6000
	s_addc_u32 s99, s99, 0
	global_load_dword v87, v200, s[98:99]
	s_add_u32 s98, s98, 0x6000
	s_addc_u32 s99, s99, 0
	global_load_dword v88, v200, s[98:99]
	s_add_u32 s98, s98, 0x6000
	s_addc_u32 s99, s99, 0
	global_load_dword v89, v200, s[98:99]
	s_add_u32 s98, s98, 0x6000
	s_addc_u32 s99, s99, 0
	global_load_dword v90, v200, s[98:99]
	s_add_u32 s98, s98, 0x6000
	s_addc_u32 s99, s99, 0
	global_load_dword v91, v200, s[98:99]
	s_add_u32 s98, s98, 0x6000
	s_addc_u32 s99, s99, 0
	global_load_dword v92, v200, s[98:99]
	s_add_u32 s98, s98, 0x6000
	s_addc_u32 s99, s99, 0
	global_load_dword v93, v200, s[98:99]
	s_add_u32 s98, s98, 0x6000
	s_addc_u32 s99, s99, 0
	global_load_dword v94, v200, s[98:99]
	s_add_u32 s98, s98, 0x6000
	s_addc_u32 s99, s99, 0
	global_load_dword v95, v200, s[98:99]
	s_add_u32 s98, s98, 0x6000
	s_addc_u32 s99, s99, 0
	global_load_dword v96, v200, s[98:99]
	s_add_u32 s98, s98, 0x6000
	s_addc_u32 s99, s99, 0
	global_load_dword v97, v200, s[98:99]
	s_add_u32 s98, s98, 0x6000
	s_addc_u32 s99, s99, 0
	global_load_dword v98, v200, s[98:99]
	s_add_u32 s98, s98, 0x6000
	s_addc_u32 s99, s99, 0
	global_load_dword v99, v200, s[98:99]
	s_add_u32 s98, s98, 0x6000
	s_addc_u32 s99, s99, 0
	global_load_dword v100, v200, s[98:99]
	s_add_u32 s98, s98, 0x6000
	s_addc_u32 s99, s99, 0
	global_load_dword v101, v200, s[98:99]
	s_add_u32 s98, s98, 0x6000
	s_addc_u32 s99, s99, 0
	global_load_dword v102, v200, s[98:99]
	s_add_u32 s98, s98, 0x6000
	s_addc_u32 s99, s99, 0
	global_load_dword v103, v200, s[98:99]
	s_add_u32 s98, s98, 0x6000
	s_addc_u32 s99, s99, 0
	global_load_dword v104, v200, s[98:99]
	s_add_u32 s98, s98, 0x6000
	s_addc_u32 s99, s99, 0
	global_load_dword v105, v200, s[98:99]
	s_add_u32 s98, s98, 0x6000
	s_addc_u32 s99, s99, 0
	global_load_dword v106, v200, s[98:99]
	s_add_u32 s98, s98, 0x6000
	s_addc_u32 s99, s99, 0
	global_load_dword v107, v200, s[98:99]
	s_add_u32 s98, s98, 0x6000
	s_addc_u32 s99, s99, 0
	global_load_dword v108, v200, s[98:99]
	s_add_u32 s98, s98, 0x6000
	s_addc_u32 s99, s99, 0
	global_load_dword v109, v200, s[98:99]
	s_add_u32 s98, s98, 0x6000
	s_addc_u32 s99, s99, 0
	global_load_dword v110, v200, s[98:99]
	s_add_u32 s98, s98, 0x6000
	s_addc_u32 s99, s99, 0
	global_load_dword v111, v200, s[98:99]
	s_add_u32 s98, s98, 0x6000
	s_addc_u32 s99, s99, 0
	global_load_dword v112, v200, s[98:99]
	s_add_u32 s98, s98, 0x6000
	s_addc_u32 s99, s99, 0
	global_load_dword v113, v200, s[98:99]
	s_add_u32 s98, s98, 0x6000
	s_addc_u32 s99, s99, 0
	global_load_dword v114, v200, s[98:99]
	s_add_u32 s98, s98, 0x6000
	s_addc_u32 s99, s99, 0
	global_load_dword v115, v200, s[98:99]
	s_add_u32 s98, s98, 0x6000
	s_addc_u32 s99, s99, 0
	global_load_dword v116, v200, s[98:99]
	s_add_u32 s98, s98, 0x6000
	s_addc_u32 s99, s99, 0
	global_load_dword v117, v200, s[98:99]
	s_add_u32 s98, s98, 0x6000
	s_addc_u32 s99, s99, 0
	global_load_dword v118, v200, s[98:99]
	s_add_u32 s98, s98, 0x6000
	s_addc_u32 s99, s99, 0
	global_load_dword v119, v200, s[98:99]
	s_add_u32 s98, s98, 0x6000
	s_addc_u32 s99, s99, 0
	global_load_dword v120, v200, s[98:99]
	s_add_u32 s98, s98, 0x6000
	s_addc_u32 s99, s99, 0
	global_load_dword v121, v200, s[98:99]
	s_add_u32 s98, s98, 0x6000
	s_addc_u32 s99, s99, 0
	global_load_dword v122, v200, s[98:99]
	s_add_u32 s98, s98, 0x6000
	s_addc_u32 s99, s99, 0
	global_load_dword v123, v200, s[98:99]
	s_add_u32 s98, s98, 0x6000
	s_addc_u32 s99, s99, 0
	global_load_dword v124, v200, s[98:99]
	s_add_u32 s98, s98, 0x6000
	s_addc_u32 s99, s99, 0
	global_load_dword v125, v200, s[98:99]
	s_add_u32 s98, s98, 0x6000
	s_addc_u32 s99, s99, 0
	global_load_dword v126, v200, s[98:99]
	s_add_u32 s98, s98, 0x6000
	s_addc_u32 s99, s99, 0
	global_load_dword v127, v200, s[98:99]
	s_add_u32 s98, s98, 0x6000
	s_addc_u32 s99, s99, 0
	global_load_dword v128, v200, s[98:99]
	s_add_u32 s98, s98, 0x6000
	s_addc_u32 s99, s99, 0
	global_load_dword v129, v200, s[98:99]
	s_add_u32 s98, s98, 0x6000
	s_addc_u32 s99, s99, 0
	global_load_dword v130, v200, s[98:99]
	s_add_u32 s98, s98, 0x6000
	s_addc_u32 s99, s99, 0
	global_load_dword v131, v200, s[98:99]
	s_add_u32 s98, s98, 0x6000
	s_addc_u32 s99, s99, 0
	global_load_dword v132, v200, s[98:99]
	s_add_u32 s98, s98, 0x6000
	s_addc_u32 s99, s99, 0
	global_load_dword v133, v200, s[98:99]
	s_add_u32 s98, s98, 0x6000
	s_addc_u32 s99, s99, 0
	global_load_dword v134, v200, s[98:99]
	s_add_u32 s98, s98, 0x6000
	s_addc_u32 s99, s99, 0
	global_load_dword v135, v200, s[98:99]
	s_add_u32 s98, s98, 0x6000
	s_addc_u32 s99, s99, 0
	global_load_dword v136, v200, s[98:99]
	s_add_u32 s98, s98, 0x6000
	s_addc_u32 s99, s99, 0
	global_load_dword v137, v200, s[98:99]
	s_add_u32 s98, s98, 0x6000
	s_addc_u32 s99, s99, 0
	global_load_dword v138, v200, s[98:99]
	s_add_u32 s98, s98, 0x6000
	s_addc_u32 s99, s99, 0
	global_load_dword v139, v200, s[98:99]
	s_add_u32 s98, s98, 0x6000
	s_addc_u32 s99, s99, 0
	global_load_dword v140, v200, s[98:99]
	s_add_u32 s98, s98, 0x6000
	s_addc_u32 s99, s99, 0
	global_load_dword v141, v200, s[98:99]
	s_add_u32 s98, s98, 0x6000
	s_addc_u32 s99, s99, 0
	global_load_dword v142, v200, s[98:99]
	s_add_u32 s98, s98, 0x6000
	s_addc_u32 s99, s99, 0
	global_load_dword v143, v200, s[98:99]
	s_add_u32 s98, s98, 0x6000
	s_addc_u32 s99, s99, 0
	ds_read_b128 v[144:147], v35
	ds_read_b128 v[148:151], v35 offset:4096
	ds_read_b128 v[152:155], v35 offset:8192
	s_waitcnt vmcnt(32)
	ds_read_b128 v[156:159], v35 offset:16
	ds_read_b128 v[160:163], v35 offset:4112
	ds_read_b128 v[164:167], v35 offset:8208
	s_waitcnt lgkmcnt(3)
	v_fmac_f32_e32 v30, v80, v144
	v_fmac_f32_e32 v34, v80, v148
	v_fmac_f32_e32 v31, v80, v152
	v_fmac_f32_e32 v30, v81, v145
	v_fmac_f32_e32 v34, v81, v149
	v_fmac_f32_e32 v31, v81, v153
	v_fmac_f32_e32 v30, v82, v146
	v_fmac_f32_e32 v34, v82, v150
	v_fmac_f32_e32 v31, v82, v154
	v_fmac_f32_e32 v30, v83, v147
	v_fmac_f32_e32 v34, v83, v151
	v_fmac_f32_e32 v31, v83, v155
	ds_read_b128 v[144:147], v35 offset:32
	ds_read_b128 v[148:151], v35 offset:4128
	ds_read_b128 v[152:155], v35 offset:8224
	s_waitcnt lgkmcnt(3)
	v_fmac_f32_e32 v30, v84, v156
	v_fmac_f32_e32 v34, v84, v160
	v_fmac_f32_e32 v31, v84, v164
	v_fmac_f32_e32 v30, v85, v157
	v_fmac_f32_e32 v34, v85, v161
	v_fmac_f32_e32 v31, v85, v165
	v_fmac_f32_e32 v30, v86, v158
	v_fmac_f32_e32 v34, v86, v162
	v_fmac_f32_e32 v31, v86, v166
	v_fmac_f32_e32 v30, v87, v159
	v_fmac_f32_e32 v34, v87, v163
	v_fmac_f32_e32 v31, v87, v167
	ds_read_b128 v[156:159], v35 offset:48
	ds_read_b128 v[160:163], v35 offset:4144
	ds_read_b128 v[164:167], v35 offset:8240
	s_waitcnt lgkmcnt(3)
	v_fmac_f32_e32 v30, v88, v144
	v_fmac_f32_e32 v34, v88, v148
	v_fmac_f32_e32 v31, v88, v152
	v_fmac_f32_e32 v30, v89, v145
	v_fmac_f32_e32 v34, v89, v149
	v_fmac_f32_e32 v31, v89, v153
	v_fmac_f32_e32 v30, v90, v146
	v_fmac_f32_e32 v34, v90, v150
	v_fmac_f32_e32 v31, v90, v154
	v_fmac_f32_e32 v30, v91, v147
	v_fmac_f32_e32 v34, v91, v151
	v_fmac_f32_e32 v31, v91, v155
	ds_read_b128 v[144:147], v35 offset:64
	ds_read_b128 v[148:151], v35 offset:4160
	ds_read_b128 v[152:155], v35 offset:8256
	s_waitcnt lgkmcnt(3)
	v_fmac_f32_e32 v30, v92, v156
	v_fmac_f32_e32 v34, v92, v160
	v_fmac_f32_e32 v31, v92, v164
	v_fmac_f32_e32 v30, v93, v157
	v_fmac_f32_e32 v34, v93, v161
	v_fmac_f32_e32 v31, v93, v165
	v_fmac_f32_e32 v30, v94, v158
	v_fmac_f32_e32 v34, v94, v162
	v_fmac_f32_e32 v31, v94, v166
	v_fmac_f32_e32 v30, v95, v159
	v_fmac_f32_e32 v34, v95, v163
	v_fmac_f32_e32 v31, v95, v167
	ds_read_b128 v[156:159], v35 offset:80
	ds_read_b128 v[160:163], v35 offset:4176
	ds_read_b128 v[164:167], v35 offset:8272
	s_waitcnt lgkmcnt(3)
	v_fmac_f32_e32 v30, v96, v144
	v_fmac_f32_e32 v34, v96, v148
	v_fmac_f32_e32 v31, v96, v152
	v_fmac_f32_e32 v30, v97, v145
	v_fmac_f32_e32 v34, v97, v149
	v_fmac_f32_e32 v31, v97, v153
	v_fmac_f32_e32 v30, v98, v146
	v_fmac_f32_e32 v34, v98, v150
	v_fmac_f32_e32 v31, v98, v154
	v_fmac_f32_e32 v30, v99, v147
	v_fmac_f32_e32 v34, v99, v151
	v_fmac_f32_e32 v31, v99, v155
	ds_read_b128 v[144:147], v35 offset:96
	ds_read_b128 v[148:151], v35 offset:4192
	ds_read_b128 v[152:155], v35 offset:8288
	s_waitcnt lgkmcnt(3)
	v_fmac_f32_e32 v30, v100, v156
	v_fmac_f32_e32 v34, v100, v160
	v_fmac_f32_e32 v31, v100, v164
	v_fmac_f32_e32 v30, v101, v157
	v_fmac_f32_e32 v34, v101, v161
	v_fmac_f32_e32 v31, v101, v165
	v_fmac_f32_e32 v30, v102, v158
	v_fmac_f32_e32 v34, v102, v162
	v_fmac_f32_e32 v31, v102, v166
	v_fmac_f32_e32 v30, v103, v159
	v_fmac_f32_e32 v34, v103, v163
	v_fmac_f32_e32 v31, v103, v167
	ds_read_b128 v[156:159], v35 offset:112
	ds_read_b128 v[160:163], v35 offset:4208
	ds_read_b128 v[164:167], v35 offset:8304
	s_waitcnt lgkmcnt(3)
	v_fmac_f32_e32 v30, v104, v144
	v_fmac_f32_e32 v34, v104, v148
	v_fmac_f32_e32 v31, v104, v152
	v_fmac_f32_e32 v30, v105, v145
	v_fmac_f32_e32 v34, v105, v149
	v_fmac_f32_e32 v31, v105, v153
	v_fmac_f32_e32 v30, v106, v146
	v_fmac_f32_e32 v34, v106, v150
	v_fmac_f32_e32 v31, v106, v154
	v_fmac_f32_e32 v30, v107, v147
	v_fmac_f32_e32 v34, v107, v151
	v_fmac_f32_e32 v31, v107, v155
	ds_read_b128 v[144:147], v35 offset:128
	ds_read_b128 v[148:151], v35 offset:4224
	ds_read_b128 v[152:155], v35 offset:8320
	s_waitcnt lgkmcnt(3)
	v_fmac_f32_e32 v30, v108, v156
	v_fmac_f32_e32 v34, v108, v160
	v_fmac_f32_e32 v31, v108, v164
	v_fmac_f32_e32 v30, v109, v157
	v_fmac_f32_e32 v34, v109, v161
	v_fmac_f32_e32 v31, v109, v165
	v_fmac_f32_e32 v30, v110, v158
	v_fmac_f32_e32 v34, v110, v162
	v_fmac_f32_e32 v31, v110, v166
	v_fmac_f32_e32 v30, v111, v159
	v_fmac_f32_e32 v34, v111, v163
	v_fmac_f32_e32 v31, v111, v167
	global_load_dword v80, v200, s[98:99]
	s_add_u32 s98, s98, 0x6000
	s_addc_u32 s99, s99, 0
	global_load_dword v81, v200, s[98:99]
	s_add_u32 s98, s98, 0x6000
	s_addc_u32 s99, s99, 0
	global_load_dword v82, v200, s[98:99]
	s_add_u32 s98, s98, 0x6000
	s_addc_u32 s99, s99, 0
	global_load_dword v83, v200, s[98:99]
	s_add_u32 s98, s98, 0x6000
	s_addc_u32 s99, s99, 0
	global_load_dword v84, v200, s[98:99]
	s_add_u32 s98, s98, 0x6000
	s_addc_u32 s99, s99, 0
	global_load_dword v85, v200, s[98:99]
	s_add_u32 s98, s98, 0x6000
	s_addc_u32 s99, s99, 0
	global_load_dword v86, v200, s[98:99]
	s_add_u32 s98, s98, 0x6000
	s_addc_u32 s99, s99, 0
	global_load_dword v87, v200, s[98:99]
	s_add_u32 s98, s98, 0x6000
	s_addc_u32 s99, s99, 0
	global_load_dword v88, v200, s[98:99]
	s_add_u32 s98, s98, 0x6000
	s_addc_u32 s99, s99, 0
	global_load_dword v89, v200, s[98:99]
	s_add_u32 s98, s98, 0x6000
	s_addc_u32 s99, s99, 0
	global_load_dword v90, v200, s[98:99]
	s_add_u32 s98, s98, 0x6000
	s_addc_u32 s99, s99, 0
	global_load_dword v91, v200, s[98:99]
	s_add_u32 s98, s98, 0x6000
	s_addc_u32 s99, s99, 0
	global_load_dword v92, v200, s[98:99]
	s_add_u32 s98, s98, 0x6000
	s_addc_u32 s99, s99, 0
	global_load_dword v93, v200, s[98:99]
	s_add_u32 s98, s98, 0x6000
	s_addc_u32 s99, s99, 0
	global_load_dword v94, v200, s[98:99]
	s_add_u32 s98, s98, 0x6000
	s_addc_u32 s99, s99, 0
	global_load_dword v95, v200, s[98:99]
	s_add_u32 s98, s98, 0x6000
	s_addc_u32 s99, s99, 0
	global_load_dword v96, v200, s[98:99]
	s_add_u32 s98, s98, 0x6000
	s_addc_u32 s99, s99, 0
	global_load_dword v97, v200, s[98:99]
	s_add_u32 s98, s98, 0x6000
	s_addc_u32 s99, s99, 0
	global_load_dword v98, v200, s[98:99]
	s_add_u32 s98, s98, 0x6000
	s_addc_u32 s99, s99, 0
	global_load_dword v99, v200, s[98:99]
	s_add_u32 s98, s98, 0x6000
	s_addc_u32 s99, s99, 0
	global_load_dword v100, v200, s[98:99]
	s_add_u32 s98, s98, 0x6000
	s_addc_u32 s99, s99, 0
	global_load_dword v101, v200, s[98:99]
	s_add_u32 s98, s98, 0x6000
	s_addc_u32 s99, s99, 0
	global_load_dword v102, v200, s[98:99]
	s_add_u32 s98, s98, 0x6000
	s_addc_u32 s99, s99, 0
	global_load_dword v103, v200, s[98:99]
	s_add_u32 s98, s98, 0x6000
	s_addc_u32 s99, s99, 0
	global_load_dword v104, v200, s[98:99]
	s_add_u32 s98, s98, 0x6000
	s_addc_u32 s99, s99, 0
	global_load_dword v105, v200, s[98:99]
	s_add_u32 s98, s98, 0x6000
	s_addc_u32 s99, s99, 0
	global_load_dword v106, v200, s[98:99]
	s_add_u32 s98, s98, 0x6000
	s_addc_u32 s99, s99, 0
	global_load_dword v107, v200, s[98:99]
	s_add_u32 s98, s98, 0x6000
	s_addc_u32 s99, s99, 0
	global_load_dword v108, v200, s[98:99]
	s_add_u32 s98, s98, 0x6000
	s_addc_u32 s99, s99, 0
	global_load_dword v109, v200, s[98:99]
	s_add_u32 s98, s98, 0x6000
	s_addc_u32 s99, s99, 0
	global_load_dword v110, v200, s[98:99]
	s_add_u32 s98, s98, 0x6000
	s_addc_u32 s99, s99, 0
	global_load_dword v111, v200, s[98:99]
	s_add_u32 s98, s98, 0x6000
	s_addc_u32 s99, s99, 0
	s_waitcnt vmcnt(32)
	ds_read_b128 v[156:159], v35 offset:144
	ds_read_b128 v[160:163], v35 offset:4240
	ds_read_b128 v[164:167], v35 offset:8336
	s_waitcnt lgkmcnt(3)
	v_fmac_f32_e32 v30, v112, v144
	v_fmac_f32_e32 v34, v112, v148
	v_fmac_f32_e32 v31, v112, v152
	v_fmac_f32_e32 v30, v113, v145
	v_fmac_f32_e32 v34, v113, v149
	v_fmac_f32_e32 v31, v113, v153
	v_fmac_f32_e32 v30, v114, v146
	v_fmac_f32_e32 v34, v114, v150
	v_fmac_f32_e32 v31, v114, v154
	v_fmac_f32_e32 v30, v115, v147
	v_fmac_f32_e32 v34, v115, v151
	v_fmac_f32_e32 v31, v115, v155
	ds_read_b128 v[144:147], v35 offset:160
	ds_read_b128 v[148:151], v35 offset:4256
	ds_read_b128 v[152:155], v35 offset:8352
	s_waitcnt lgkmcnt(3)
	v_fmac_f32_e32 v30, v116, v156
	v_fmac_f32_e32 v34, v116, v160
	v_fmac_f32_e32 v31, v116, v164
	v_fmac_f32_e32 v30, v117, v157
	v_fmac_f32_e32 v34, v117, v161
	v_fmac_f32_e32 v31, v117, v165
	v_fmac_f32_e32 v30, v118, v158
	v_fmac_f32_e32 v34, v118, v162
	v_fmac_f32_e32 v31, v118, v166
	v_fmac_f32_e32 v30, v119, v159
	v_fmac_f32_e32 v34, v119, v163
	v_fmac_f32_e32 v31, v119, v167
	ds_read_b128 v[156:159], v35 offset:176
	ds_read_b128 v[160:163], v35 offset:4272
	ds_read_b128 v[164:167], v35 offset:8368
	s_waitcnt lgkmcnt(3)
	v_fmac_f32_e32 v30, v120, v144
	v_fmac_f32_e32 v34, v120, v148
	v_fmac_f32_e32 v31, v120, v152
	v_fmac_f32_e32 v30, v121, v145
	v_fmac_f32_e32 v34, v121, v149
	v_fmac_f32_e32 v31, v121, v153
	v_fmac_f32_e32 v30, v122, v146
	v_fmac_f32_e32 v34, v122, v150
	v_fmac_f32_e32 v31, v122, v154
	v_fmac_f32_e32 v30, v123, v147
	v_fmac_f32_e32 v34, v123, v151
	v_fmac_f32_e32 v31, v123, v155
	ds_read_b128 v[144:147], v35 offset:192
	ds_read_b128 v[148:151], v35 offset:4288
	ds_read_b128 v[152:155], v35 offset:8384
	s_waitcnt lgkmcnt(3)
	v_fmac_f32_e32 v30, v124, v156
	v_fmac_f32_e32 v34, v124, v160
	v_fmac_f32_e32 v31, v124, v164
	v_fmac_f32_e32 v30, v125, v157
	v_fmac_f32_e32 v34, v125, v161
	v_fmac_f32_e32 v31, v125, v165
	v_fmac_f32_e32 v30, v126, v158
	v_fmac_f32_e32 v34, v126, v162
	v_fmac_f32_e32 v31, v126, v166
	v_fmac_f32_e32 v30, v127, v159
	v_fmac_f32_e32 v34, v127, v163
	v_fmac_f32_e32 v31, v127, v167
	ds_read_b128 v[156:159], v35 offset:208
	ds_read_b128 v[160:163], v35 offset:4304
	ds_read_b128 v[164:167], v35 offset:8400
	s_waitcnt lgkmcnt(3)
	v_fmac_f32_e32 v30, v128, v144
	v_fmac_f32_e32 v34, v128, v148
	v_fmac_f32_e32 v31, v128, v152
	v_fmac_f32_e32 v30, v129, v145
	v_fmac_f32_e32 v34, v129, v149
	v_fmac_f32_e32 v31, v129, v153
	v_fmac_f32_e32 v30, v130, v146
	v_fmac_f32_e32 v34, v130, v150
	v_fmac_f32_e32 v31, v130, v154
	v_fmac_f32_e32 v30, v131, v147
	v_fmac_f32_e32 v34, v131, v151
	v_fmac_f32_e32 v31, v131, v155
	ds_read_b128 v[144:147], v35 offset:224
	ds_read_b128 v[148:151], v35 offset:4320
	ds_read_b128 v[152:155], v35 offset:8416
	s_waitcnt lgkmcnt(3)
	v_fmac_f32_e32 v30, v132, v156
	v_fmac_f32_e32 v34, v132, v160
	v_fmac_f32_e32 v31, v132, v164
	v_fmac_f32_e32 v30, v133, v157
	v_fmac_f32_e32 v34, v133, v161
	v_fmac_f32_e32 v31, v133, v165
	v_fmac_f32_e32 v30, v134, v158
	v_fmac_f32_e32 v34, v134, v162
	v_fmac_f32_e32 v31, v134, v166
	v_fmac_f32_e32 v30, v135, v159
	v_fmac_f32_e32 v34, v135, v163
	v_fmac_f32_e32 v31, v135, v167
	ds_read_b128 v[156:159], v35 offset:240
	ds_read_b128 v[160:163], v35 offset:4336
	ds_read_b128 v[164:167], v35 offset:8432
	s_waitcnt lgkmcnt(3)
	v_fmac_f32_e32 v30, v136, v144
	v_fmac_f32_e32 v34, v136, v148
	v_fmac_f32_e32 v31, v136, v152
	v_fmac_f32_e32 v30, v137, v145
	v_fmac_f32_e32 v34, v137, v149
	v_fmac_f32_e32 v31, v137, v153
	v_fmac_f32_e32 v30, v138, v146
	v_fmac_f32_e32 v34, v138, v150
	v_fmac_f32_e32 v31, v138, v154
	v_fmac_f32_e32 v30, v139, v147
	v_fmac_f32_e32 v34, v139, v151
	v_fmac_f32_e32 v31, v139, v155
	ds_read_b128 v[144:147], v35 offset:256
	ds_read_b128 v[148:151], v35 offset:4352
	ds_read_b128 v[152:155], v35 offset:8448
	s_waitcnt lgkmcnt(3)
	v_fmac_f32_e32 v30, v140, v156
	v_fmac_f32_e32 v34, v140, v160
	v_fmac_f32_e32 v31, v140, v164
	v_fmac_f32_e32 v30, v141, v157
	v_fmac_f32_e32 v34, v141, v161
	v_fmac_f32_e32 v31, v141, v165
	v_fmac_f32_e32 v30, v142, v158
	v_fmac_f32_e32 v34, v142, v162
	v_fmac_f32_e32 v31, v142, v166
	v_fmac_f32_e32 v30, v143, v159
	v_fmac_f32_e32 v34, v143, v163
	v_fmac_f32_e32 v31, v143, v167
	global_load_dword v112, v200, s[98:99]
	s_add_u32 s98, s98, 0x6000
	s_addc_u32 s99, s99, 0
	global_load_dword v113, v200, s[98:99]
	s_add_u32 s98, s98, 0x6000
	s_addc_u32 s99, s99, 0
	global_load_dword v114, v200, s[98:99]
	s_add_u32 s98, s98, 0x6000
	s_addc_u32 s99, s99, 0
	global_load_dword v115, v200, s[98:99]
	s_add_u32 s98, s98, 0x6000
	s_addc_u32 s99, s99, 0
	global_load_dword v116, v200, s[98:99]
	s_add_u32 s98, s98, 0x6000
	s_addc_u32 s99, s99, 0
	global_load_dword v117, v200, s[98:99]
	s_add_u32 s98, s98, 0x6000
	s_addc_u32 s99, s99, 0
	global_load_dword v118, v200, s[98:99]
	s_add_u32 s98, s98, 0x6000
	s_addc_u32 s99, s99, 0
	global_load_dword v119, v200, s[98:99]
	s_add_u32 s98, s98, 0x6000
	s_addc_u32 s99, s99, 0
	global_load_dword v120, v200, s[98:99]
	s_add_u32 s98, s98, 0x6000
	s_addc_u32 s99, s99, 0
	global_load_dword v121, v200, s[98:99]
	s_add_u32 s98, s98, 0x6000
	s_addc_u32 s99, s99, 0
	global_load_dword v122, v200, s[98:99]
	s_add_u32 s98, s98, 0x6000
	s_addc_u32 s99, s99, 0
	global_load_dword v123, v200, s[98:99]
	s_add_u32 s98, s98, 0x6000
	s_addc_u32 s99, s99, 0
	global_load_dword v124, v200, s[98:99]
	s_add_u32 s98, s98, 0x6000
	s_addc_u32 s99, s99, 0
	global_load_dword v125, v200, s[98:99]
	s_add_u32 s98, s98, 0x6000
	s_addc_u32 s99, s99, 0
	global_load_dword v126, v200, s[98:99]
	s_add_u32 s98, s98, 0x6000
	s_addc_u32 s99, s99, 0
	global_load_dword v127, v200, s[98:99]
	s_add_u32 s98, s98, 0x6000
	s_addc_u32 s99, s99, 0
	global_load_dword v128, v200, s[98:99]
	s_add_u32 s98, s98, 0x6000
	s_addc_u32 s99, s99, 0
	global_load_dword v129, v200, s[98:99]
	s_add_u32 s98, s98, 0x6000
	s_addc_u32 s99, s99, 0
	global_load_dword v130, v200, s[98:99]
	s_add_u32 s98, s98, 0x6000
	s_addc_u32 s99, s99, 0
	global_load_dword v131, v200, s[98:99]
	s_add_u32 s98, s98, 0x6000
	s_addc_u32 s99, s99, 0
	global_load_dword v132, v200, s[98:99]
	s_add_u32 s98, s98, 0x6000
	s_addc_u32 s99, s99, 0
	global_load_dword v133, v200, s[98:99]
	s_add_u32 s98, s98, 0x6000
	s_addc_u32 s99, s99, 0
	global_load_dword v134, v200, s[98:99]
	s_add_u32 s98, s98, 0x6000
	s_addc_u32 s99, s99, 0
	global_load_dword v135, v200, s[98:99]
	s_add_u32 s98, s98, 0x6000
	s_addc_u32 s99, s99, 0
	global_load_dword v136, v200, s[98:99]
	s_add_u32 s98, s98, 0x6000
	s_addc_u32 s99, s99, 0
	global_load_dword v137, v200, s[98:99]
	s_add_u32 s98, s98, 0x6000
	s_addc_u32 s99, s99, 0
	global_load_dword v138, v200, s[98:99]
	s_add_u32 s98, s98, 0x6000
	s_addc_u32 s99, s99, 0
	global_load_dword v139, v200, s[98:99]
	s_add_u32 s98, s98, 0x6000
	s_addc_u32 s99, s99, 0
	global_load_dword v140, v200, s[98:99]
	s_add_u32 s98, s98, 0x6000
	s_addc_u32 s99, s99, 0
	global_load_dword v141, v200, s[98:99]
	s_add_u32 s98, s98, 0x6000
	s_addc_u32 s99, s99, 0
	global_load_dword v142, v200, s[98:99]
	s_add_u32 s98, s98, 0x6000
	s_addc_u32 s99, s99, 0
	global_load_dword v143, v200, s[98:99]
	s_add_u32 s98, s98, 0x6000
	s_addc_u32 s99, s99, 0
	s_waitcnt vmcnt(32)
	ds_read_b128 v[156:159], v35 offset:272
	ds_read_b128 v[160:163], v35 offset:4368
	ds_read_b128 v[164:167], v35 offset:8464
	s_waitcnt lgkmcnt(3)
	v_fmac_f32_e32 v30, v80, v144
	v_fmac_f32_e32 v34, v80, v148
	v_fmac_f32_e32 v31, v80, v152
	v_fmac_f32_e32 v30, v81, v145
	v_fmac_f32_e32 v34, v81, v149
	v_fmac_f32_e32 v31, v81, v153
	v_fmac_f32_e32 v30, v82, v146
	v_fmac_f32_e32 v34, v82, v150
	v_fmac_f32_e32 v31, v82, v154
	v_fmac_f32_e32 v30, v83, v147
	v_fmac_f32_e32 v34, v83, v151
	v_fmac_f32_e32 v31, v83, v155
	ds_read_b128 v[144:147], v35 offset:288
	ds_read_b128 v[148:151], v35 offset:4384
	ds_read_b128 v[152:155], v35 offset:8480
	s_waitcnt lgkmcnt(3)
	v_fmac_f32_e32 v30, v84, v156
	v_fmac_f32_e32 v34, v84, v160
	v_fmac_f32_e32 v31, v84, v164
	v_fmac_f32_e32 v30, v85, v157
	v_fmac_f32_e32 v34, v85, v161
	v_fmac_f32_e32 v31, v85, v165
	v_fmac_f32_e32 v30, v86, v158
	v_fmac_f32_e32 v34, v86, v162
	v_fmac_f32_e32 v31, v86, v166
	v_fmac_f32_e32 v30, v87, v159
	v_fmac_f32_e32 v34, v87, v163
	v_fmac_f32_e32 v31, v87, v167
	ds_read_b128 v[156:159], v35 offset:304
	ds_read_b128 v[160:163], v35 offset:4400
	ds_read_b128 v[164:167], v35 offset:8496
	s_waitcnt lgkmcnt(3)
	v_fmac_f32_e32 v30, v88, v144
	v_fmac_f32_e32 v34, v88, v148
	v_fmac_f32_e32 v31, v88, v152
	v_fmac_f32_e32 v30, v89, v145
	v_fmac_f32_e32 v34, v89, v149
	v_fmac_f32_e32 v31, v89, v153
	v_fmac_f32_e32 v30, v90, v146
	v_fmac_f32_e32 v34, v90, v150
	v_fmac_f32_e32 v31, v90, v154
	v_fmac_f32_e32 v30, v91, v147
	v_fmac_f32_e32 v34, v91, v151
	v_fmac_f32_e32 v31, v91, v155
	ds_read_b128 v[144:147], v35 offset:320
	ds_read_b128 v[148:151], v35 offset:4416
	ds_read_b128 v[152:155], v35 offset:8512
	s_waitcnt lgkmcnt(3)
	v_fmac_f32_e32 v30, v92, v156
	v_fmac_f32_e32 v34, v92, v160
	v_fmac_f32_e32 v31, v92, v164
	v_fmac_f32_e32 v30, v93, v157
	v_fmac_f32_e32 v34, v93, v161
	v_fmac_f32_e32 v31, v93, v165
	v_fmac_f32_e32 v30, v94, v158
	v_fmac_f32_e32 v34, v94, v162
	v_fmac_f32_e32 v31, v94, v166
	v_fmac_f32_e32 v30, v95, v159
	v_fmac_f32_e32 v34, v95, v163
	v_fmac_f32_e32 v31, v95, v167
	ds_read_b128 v[156:159], v35 offset:336
	ds_read_b128 v[160:163], v35 offset:4432
	ds_read_b128 v[164:167], v35 offset:8528
	s_waitcnt lgkmcnt(3)
	v_fmac_f32_e32 v30, v96, v144
	v_fmac_f32_e32 v34, v96, v148
	v_fmac_f32_e32 v31, v96, v152
	v_fmac_f32_e32 v30, v97, v145
	v_fmac_f32_e32 v34, v97, v149
	v_fmac_f32_e32 v31, v97, v153
	v_fmac_f32_e32 v30, v98, v146
	v_fmac_f32_e32 v34, v98, v150
	v_fmac_f32_e32 v31, v98, v154
	v_fmac_f32_e32 v30, v99, v147
	v_fmac_f32_e32 v34, v99, v151
	v_fmac_f32_e32 v31, v99, v155
	ds_read_b128 v[144:147], v35 offset:352
	ds_read_b128 v[148:151], v35 offset:4448
	ds_read_b128 v[152:155], v35 offset:8544
	s_waitcnt lgkmcnt(3)
	v_fmac_f32_e32 v30, v100, v156
	v_fmac_f32_e32 v34, v100, v160
	v_fmac_f32_e32 v31, v100, v164
	v_fmac_f32_e32 v30, v101, v157
	v_fmac_f32_e32 v34, v101, v161
	v_fmac_f32_e32 v31, v101, v165
	v_fmac_f32_e32 v30, v102, v158
	v_fmac_f32_e32 v34, v102, v162
	v_fmac_f32_e32 v31, v102, v166
	v_fmac_f32_e32 v30, v103, v159
	v_fmac_f32_e32 v34, v103, v163
	v_fmac_f32_e32 v31, v103, v167
	ds_read_b128 v[156:159], v35 offset:368
	ds_read_b128 v[160:163], v35 offset:4464
	ds_read_b128 v[164:167], v35 offset:8560
	s_waitcnt lgkmcnt(3)
	v_fmac_f32_e32 v30, v104, v144
	v_fmac_f32_e32 v34, v104, v148
	v_fmac_f32_e32 v31, v104, v152
	v_fmac_f32_e32 v30, v105, v145
	v_fmac_f32_e32 v34, v105, v149
	v_fmac_f32_e32 v31, v105, v153
	v_fmac_f32_e32 v30, v106, v146
	v_fmac_f32_e32 v34, v106, v150
	v_fmac_f32_e32 v31, v106, v154
	v_fmac_f32_e32 v30, v107, v147
	v_fmac_f32_e32 v34, v107, v151
	v_fmac_f32_e32 v31, v107, v155
	ds_read_b128 v[144:147], v35 offset:384
	ds_read_b128 v[148:151], v35 offset:4480
	ds_read_b128 v[152:155], v35 offset:8576
	s_waitcnt lgkmcnt(3)
	v_fmac_f32_e32 v30, v108, v156
	v_fmac_f32_e32 v34, v108, v160
	v_fmac_f32_e32 v31, v108, v164
	v_fmac_f32_e32 v30, v109, v157
	v_fmac_f32_e32 v34, v109, v161
	v_fmac_f32_e32 v31, v109, v165
	v_fmac_f32_e32 v30, v110, v158
	v_fmac_f32_e32 v34, v110, v162
	v_fmac_f32_e32 v31, v110, v166
	v_fmac_f32_e32 v30, v111, v159
	v_fmac_f32_e32 v34, v111, v163
	v_fmac_f32_e32 v31, v111, v167
	s_waitcnt vmcnt(0)
	ds_read_b128 v[156:159], v35 offset:400
	ds_read_b128 v[160:163], v35 offset:4496
	ds_read_b128 v[164:167], v35 offset:8592
	s_waitcnt lgkmcnt(3)
	v_fmac_f32_e32 v30, v112, v144
	v_fmac_f32_e32 v34, v112, v148
	v_fmac_f32_e32 v31, v112, v152
	v_fmac_f32_e32 v30, v113, v145
	v_fmac_f32_e32 v34, v113, v149
	v_fmac_f32_e32 v31, v113, v153
	v_fmac_f32_e32 v30, v114, v146
	v_fmac_f32_e32 v34, v114, v150
	v_fmac_f32_e32 v31, v114, v154
	v_fmac_f32_e32 v30, v115, v147
	v_fmac_f32_e32 v34, v115, v151
	v_fmac_f32_e32 v31, v115, v155
	ds_read_b128 v[144:147], v35 offset:416
	ds_read_b128 v[148:151], v35 offset:4512
	ds_read_b128 v[152:155], v35 offset:8608
	s_waitcnt lgkmcnt(3)
	v_fmac_f32_e32 v30, v116, v156
	v_fmac_f32_e32 v34, v116, v160
	v_fmac_f32_e32 v31, v116, v164
	v_fmac_f32_e32 v30, v117, v157
	v_fmac_f32_e32 v34, v117, v161
	v_fmac_f32_e32 v31, v117, v165
	v_fmac_f32_e32 v30, v118, v158
	v_fmac_f32_e32 v34, v118, v162
	v_fmac_f32_e32 v31, v118, v166
	v_fmac_f32_e32 v30, v119, v159
	v_fmac_f32_e32 v34, v119, v163
	v_fmac_f32_e32 v31, v119, v167
	ds_read_b128 v[156:159], v35 offset:432
	ds_read_b128 v[160:163], v35 offset:4528
	ds_read_b128 v[164:167], v35 offset:8624
	s_waitcnt lgkmcnt(3)
	v_fmac_f32_e32 v30, v120, v144
	v_fmac_f32_e32 v34, v120, v148
	v_fmac_f32_e32 v31, v120, v152
	v_fmac_f32_e32 v30, v121, v145
	v_fmac_f32_e32 v34, v121, v149
	v_fmac_f32_e32 v31, v121, v153
	v_fmac_f32_e32 v30, v122, v146
	v_fmac_f32_e32 v34, v122, v150
	v_fmac_f32_e32 v31, v122, v154
	v_fmac_f32_e32 v30, v123, v147
	v_fmac_f32_e32 v34, v123, v151
	v_fmac_f32_e32 v31, v123, v155
	ds_read_b128 v[144:147], v35 offset:448
	ds_read_b128 v[148:151], v35 offset:4544
	ds_read_b128 v[152:155], v35 offset:8640
	s_waitcnt lgkmcnt(3)
	v_fmac_f32_e32 v30, v124, v156
	v_fmac_f32_e32 v34, v124, v160
	v_fmac_f32_e32 v31, v124, v164
	v_fmac_f32_e32 v30, v125, v157
	v_fmac_f32_e32 v34, v125, v161
	v_fmac_f32_e32 v31, v125, v165
	v_fmac_f32_e32 v30, v126, v158
	v_fmac_f32_e32 v34, v126, v162
	v_fmac_f32_e32 v31, v126, v166
	v_fmac_f32_e32 v30, v127, v159
	v_fmac_f32_e32 v34, v127, v163
	v_fmac_f32_e32 v31, v127, v167
	ds_read_b128 v[156:159], v35 offset:464
	ds_read_b128 v[160:163], v35 offset:4560
	ds_read_b128 v[164:167], v35 offset:8656
	s_waitcnt lgkmcnt(3)
	v_fmac_f32_e32 v30, v128, v144
	v_fmac_f32_e32 v34, v128, v148
	v_fmac_f32_e32 v31, v128, v152
	v_fmac_f32_e32 v30, v129, v145
	v_fmac_f32_e32 v34, v129, v149
	v_fmac_f32_e32 v31, v129, v153
	v_fmac_f32_e32 v30, v130, v146
	v_fmac_f32_e32 v34, v130, v150
	v_fmac_f32_e32 v31, v130, v154
	v_fmac_f32_e32 v30, v131, v147
	v_fmac_f32_e32 v34, v131, v151
	v_fmac_f32_e32 v31, v131, v155
	ds_read_b128 v[144:147], v35 offset:480
	ds_read_b128 v[148:151], v35 offset:4576
	ds_read_b128 v[152:155], v35 offset:8672
	s_waitcnt lgkmcnt(3)
	v_fmac_f32_e32 v30, v132, v156
	v_fmac_f32_e32 v34, v132, v160
	v_fmac_f32_e32 v31, v132, v164
	v_fmac_f32_e32 v30, v133, v157
	v_fmac_f32_e32 v34, v133, v161
	v_fmac_f32_e32 v31, v133, v165
	v_fmac_f32_e32 v30, v134, v158
	v_fmac_f32_e32 v34, v134, v162
	v_fmac_f32_e32 v31, v134, v166
	v_fmac_f32_e32 v30, v135, v159
	v_fmac_f32_e32 v34, v135, v163
	v_fmac_f32_e32 v31, v135, v167
	ds_read_b128 v[156:159], v35 offset:496
	ds_read_b128 v[160:163], v35 offset:4592
	ds_read_b128 v[164:167], v35 offset:8688
	s_waitcnt lgkmcnt(3)
	v_fmac_f32_e32 v30, v136, v144
	v_fmac_f32_e32 v34, v136, v148
	v_fmac_f32_e32 v31, v136, v152
	v_fmac_f32_e32 v30, v137, v145
	v_fmac_f32_e32 v34, v137, v149
	v_fmac_f32_e32 v31, v137, v153
	v_fmac_f32_e32 v30, v138, v146
	v_fmac_f32_e32 v34, v138, v150
	v_fmac_f32_e32 v31, v138, v154
	v_fmac_f32_e32 v30, v139, v147
	v_fmac_f32_e32 v34, v139, v151
	v_fmac_f32_e32 v31, v139, v155
	s_waitcnt lgkmcnt(0)
	v_fmac_f32_e32 v30, v140, v156
	v_fmac_f32_e32 v34, v140, v160
	v_fmac_f32_e32 v31, v140, v164
	v_fmac_f32_e32 v30, v141, v157
	v_fmac_f32_e32 v34, v141, v161
	v_fmac_f32_e32 v31, v141, v165
	v_fmac_f32_e32 v30, v142, v158
	v_fmac_f32_e32 v34, v142, v162
	v_fmac_f32_e32 v31, v142, v166
	v_fmac_f32_e32 v30, v143, v159
	v_fmac_f32_e32 v34, v143, v163
	v_fmac_f32_e32 v31, v143, v167
	ds_write2st64_b32 v19, v30, v34 offset0:52 offset1:53
	ds_write_b32 v19, v31 offset:13824
	s_waitcnt lgkmcnt(0)
	s_barrier
	s_and_saveexec_b64 s[4:5], vcc
	s_cbranch_execz .LBB0_27
	ds_read_b64 v[28:29], v23 offset:152
	s_mul_i32 s20, s39, 0x1800
	s_add_i32 s20, s20, s12
	v_or_b32_e32 v30, s20, v198
	v_ashrrev_i32_e32 v31, 31, v30
	s_waitcnt lgkmcnt(0)
	v_readfirstlane_b32 s21, v28
	v_readfirstlane_b32 s40, v29
	v_mov_b64_e32 v[40:41], s[10:11]
	v_mov_b32_e32 v28, s21
	v_mov_b32_e32 v29, s40
	v_lshl_add_u64 v[28:29], v[30:31], 2, v[28:29]
	v_mov_b32_e32 v42, v201
	ds_read2st64_b32 v[28:29], v33 offset0:52 offset1:55
	ds_read2st64_b32 v[30:31], v33 offset0:58 offset1:61
	ds_read2st64_b32 v[34:35], v33 offset0:64 offset1:67
	ds_read2st64_b32 v[36:37], v33 offset0:70 offset1:73
	v_mad_u64_u32 v[38:39], s[20:21], s39, 3, v[18:19]
	s_waitcnt lgkmcnt(3)
	v_add_f32_e32 v28, 0, v28
	v_add_f32_e32 v28, v28, v29
	s_waitcnt lgkmcnt(2)
	v_add_f32_e32 v28, v28, v30
	v_add_f32_e32 v28, v28, v31
	s_waitcnt lgkmcnt(1)
	v_add_f32_e32 v28, v28, v34
	v_add_f32_e32 v28, v28, v35
	v_mad_i64_i32 v[38:39], s[20:21], v38, s23, v[40:41]
	s_waitcnt lgkmcnt(0)
	v_add_f32_e32 v28, v28, v36
	v_lshl_add_u64 v[38:39], s[12:13], 2, v[38:39]
	v_add_f32_e32 v28, v28, v37
	s_waitcnt vmcnt(0)
	v_add_f32_e32 v30, v28, v42
	v_lshl_add_u64 v[28:29], v[38:39], 0, v[22:23]
	global_store_dword v[28:29], v30, off
	s_branch .LBB0_27
